# S_raw buffer stored in the order the prompt chain reads it, so the chain's four S_raw loads per chunk are lane-contiguous 1 KB loads
# baseline (speedup 1.0000x reference)
.LBB0_767:
	s_or_b64 exec, exec, s[28:29]
	s_and_b32 s24, s0, 0xfffff800
	s_and_b32 s27, s4, 0x7c0
	v_or_b32_e32 v2, s24, v33
	s_or_b32 s28, s27, s24
	v_or_b32_e32 v4, s27, v2
	v_add_u32_e32 v0, s28, v31
	s_and_b32 s28, s37, 3
	v_ashrrev_i32_e32 v5, 31, v4
	s_lshl_b32 s28, s28, 10
	v_lshlrev_b64 v[4:5], 12, v[4:5]
	v_or_b32_e32 v4, s28, v4
	v_or_b32_e32 v2, s24, v32
	v_lshl_add_u64 v[20:21], v[18:19], 0, v[4:5]
	v_or_b32_e32 v4, s27, v2
	v_ashrrev_i32_e32 v5, 31, v4
	v_ashrrev_i32_e32 v1, 31, v0
	v_lshlrev_b64 v[4:5], 12, v[4:5]
	v_lshlrev_b64 v[0:1], 12, v[0:1]
	v_or_b32_e32 v4, s28, v4
	v_or_b32_e32 v0, s28, v0
	v_lshl_add_u64 v[22:23], v[18:19], 0, v[4:5]
	v_mov_b32_e32 v4, 0
	v_lshl_add_u64 v[0:1], v[18:19], 0, v[0:1]
	s_mov_b64 s[28:29], 0
	v_mov_b32_e32 v5, v4
	v_mov_b32_e32 v6, v4
	v_mov_b32_e32 v7, v4
	v_mov_b32_e32 v8, v4
	v_mov_b32_e32 v9, v4
	v_mov_b32_e32 v10, v4
	v_mov_b32_e32 v11, v4
	s_sub_u32 s80, s22, 0x3a20000
	s_subb_u32 s81, s23, 0
	s_and_b32 s82, s26, 31
	s_lshl_b32 s82, s82, 6
	s_lshr_b32 s83, s37, 2
	s_lshl_b32 s83, s83, 11
	s_add_i32 s82, s82, s83
	s_and_b32 s83, s37, 3
	s_lshl_b32 s83, s83, 10
	s_lshl_b32 s84, s82, 12
	s_add_u32 s84, s84, s83
	s_add_u32 s85, s84, 0x21752000
	s_add_u32 s86, s80, s85
	s_addc_u32 s87, s81, 0
	s_add_u32 s85, s84, 0x25b52000
	s_add_u32 s88, s80, s85
	s_addc_u32 s89, s81, 0
	v_lshrrev_b32_e32 v73, 6, v201
	s_nop 0
	v_readfirstlane_b32 s90, v73
	s_lshl_b32 s91, s90, 15
	v_lshlrev_b32_e32 v72, 4, v200
	v_add_u32_e32 v72, s91, v72
	s_mul_i32 s92, s90, 0x2080
	s_add_i32 m0, s92, 0x0
	s_nop 0
	global_load_lds_dwordx4 v72, s[86:87]
	s_add_i32 m0, s92, 0x10400
	s_nop 0
	global_load_lds_dwordx4 v72, s[88:89]
	v_add_u32_e32 v72, 0x1000, v72
	s_add_i32 m0, s92, 0x410
	s_nop 0
	global_load_lds_dwordx4 v72, s[86:87]
	s_add_i32 m0, s92, 0x10810
	s_nop 0
	global_load_lds_dwordx4 v72, s[88:89]
	v_add_u32_e32 v72, 0x1000, v72
	s_add_i32 m0, s92, 0x820
	s_nop 0
	global_load_lds_dwordx4 v72, s[86:87]
	s_add_i32 m0, s92, 0x10c20
	s_nop 0
	global_load_lds_dwordx4 v72, s[88:89]
	v_add_u32_e32 v72, 0x1000, v72
	s_add_i32 m0, s92, 0xc30
	s_nop 0
	global_load_lds_dwordx4 v72, s[86:87]
	s_add_i32 m0, s92, 0x11030
	s_nop 0
	global_load_lds_dwordx4 v72, s[88:89]
	v_add_u32_e32 v72, 0x1000, v72
	s_add_i32 m0, s92, 0x1040
	s_nop 0
	global_load_lds_dwordx4 v72, s[86:87]
	s_add_i32 m0, s92, 0x11440
	s_nop 0
	global_load_lds_dwordx4 v72, s[88:89]
	v_add_u32_e32 v72, 0x1000, v72
	s_add_i32 m0, s92, 0x1450
	s_nop 0
	global_load_lds_dwordx4 v72, s[86:87]
	s_add_i32 m0, s92, 0x11850
	s_nop 0
	global_load_lds_dwordx4 v72, s[88:89]
	v_add_u32_e32 v72, 0x1000, v72
	s_add_i32 m0, s92, 0x1860
	s_nop 0
	global_load_lds_dwordx4 v72, s[86:87]
	s_add_i32 m0, s92, 0x11c60
	s_nop 0
	global_load_lds_dwordx4 v72, s[88:89]
	v_add_u32_e32 v72, 0x1000, v72
	s_add_i32 m0, s92, 0x1c70
	s_nop 0
	global_load_lds_dwordx4 v72, s[86:87]
	s_add_i32 m0, s92, 0x12070
	s_nop 0
	global_load_lds_dwordx4 v72, s[88:89]
	v_and_b32_e32 v172, 15, v200
	v_lshrrev_b32_e32 v73, 4, v200
	v_lshlrev_b32_e32 v73, 4, v73
	s_lshr_b32 s93, s90, 1
	s_lshl_b32 s93, s93, 4
	v_add_u32_e32 v173, s93, v172
	v_mul_u32_u24_e32 v173, 0x410, v173
	s_and_b32 s93, s90, 1
	s_lshl_b32 s93, s93, 5
	s_addk_i32 s93, 0x40
	v_add_u32_e32 v172, s93, v172
	v_mul_u32_u24_e32 v172, 0x410, v172
	v_add_u32_e32 v173, v173, v73
	v_add_u32_e32 v172, v172, v73
	s_waitcnt vmcnt(0)
	s_barrier
	ds_read_b128 v[76:79], v173 offset:0
	ds_read_b128 v[80:83], v172 offset:0
	ds_read_b128 v[84:87], v172 offset:16640
	ds_read_b128 v[88:91], v173 offset:64
	ds_read_b128 v[92:95], v172 offset:64
	ds_read_b128 v[96:99], v172 offset:16704
	ds_read_b128 v[100:103], v173 offset:128
	ds_read_b128 v[104:107], v172 offset:128
	ds_read_b128 v[108:111], v172 offset:16768
	ds_read_b128 v[112:115], v173 offset:192
	ds_read_b128 v[116:119], v172 offset:192
	ds_read_b128 v[120:123], v172 offset:16832
	ds_read_b128 v[124:127], v173 offset:256
	ds_read_b128 v[128:131], v172 offset:256
	ds_read_b128 v[132:135], v172 offset:16896
	ds_read_b128 v[136:139], v173 offset:320
	ds_read_b128 v[140:143], v172 offset:320
	ds_read_b128 v[144:147], v172 offset:16960
	ds_read_b128 v[148:151], v173 offset:384
	ds_read_b128 v[152:155], v172 offset:384
	ds_read_b128 v[156:159], v172 offset:17024
	ds_read_b128 v[160:163], v173 offset:448
	ds_read_b128 v[164:167], v172 offset:448
	ds_read_b128 v[168:171], v172 offset:17088
	s_waitcnt lgkmcnt(0)
	v_mfma_f32_16x16x32_bf16 v[4:7], v[76:79], v[80:83], v[4:7]
	v_mfma_f32_16x16x32_bf16 v[8:11], v[76:79], v[84:87], v[8:11]
	v_mfma_f32_16x16x32_bf16 v[4:7], v[88:91], v[92:95], v[4:7]
	v_mfma_f32_16x16x32_bf16 v[8:11], v[88:91], v[96:99], v[8:11]
	v_mfma_f32_16x16x32_bf16 v[4:7], v[100:103], v[104:107], v[4:7]
	v_mfma_f32_16x16x32_bf16 v[8:11], v[100:103], v[108:111], v[8:11]
	v_mfma_f32_16x16x32_bf16 v[4:7], v[112:115], v[116:119], v[4:7]
	v_mfma_f32_16x16x32_bf16 v[8:11], v[112:115], v[120:123], v[8:11]
	v_mfma_f32_16x16x32_bf16 v[4:7], v[124:127], v[128:131], v[4:7]
	v_mfma_f32_16x16x32_bf16 v[8:11], v[124:127], v[132:135], v[8:11]
	v_mfma_f32_16x16x32_bf16 v[4:7], v[136:139], v[140:143], v[4:7]
	v_mfma_f32_16x16x32_bf16 v[8:11], v[136:139], v[144:147], v[8:11]
	v_mfma_f32_16x16x32_bf16 v[4:7], v[148:151], v[152:155], v[4:7]
	v_mfma_f32_16x16x32_bf16 v[8:11], v[148:151], v[156:159], v[8:11]
	v_mfma_f32_16x16x32_bf16 v[4:7], v[160:163], v[164:167], v[4:7]
	v_mfma_f32_16x16x32_bf16 v[8:11], v[160:163], v[168:171], v[8:11]
	ds_read_b128 v[76:79], v173 offset:512
	ds_read_b128 v[80:83], v172 offset:512
	ds_read_b128 v[84:87], v172 offset:17152
	ds_read_b128 v[88:91], v173 offset:576
	ds_read_b128 v[92:95], v172 offset:576
	ds_read_b128 v[96:99], v172 offset:17216
	ds_read_b128 v[100:103], v173 offset:640
	ds_read_b128 v[104:107], v172 offset:640
	ds_read_b128 v[108:111], v172 offset:17280
	ds_read_b128 v[112:115], v173 offset:704
	ds_read_b128 v[116:119], v172 offset:704
	ds_read_b128 v[120:123], v172 offset:17344
	ds_read_b128 v[124:127], v173 offset:768
	ds_read_b128 v[128:131], v172 offset:768
	ds_read_b128 v[132:135], v172 offset:17408
	ds_read_b128 v[136:139], v173 offset:832
	ds_read_b128 v[140:143], v172 offset:832
	ds_read_b128 v[144:147], v172 offset:17472
	ds_read_b128 v[148:151], v173 offset:896
	ds_read_b128 v[152:155], v172 offset:896
	ds_read_b128 v[156:159], v172 offset:17536
	ds_read_b128 v[160:163], v173 offset:960
	ds_read_b128 v[164:167], v172 offset:960
	ds_read_b128 v[168:171], v172 offset:17600
	s_waitcnt lgkmcnt(0)
	v_mfma_f32_16x16x32_bf16 v[4:7], v[76:79], v[80:83], v[4:7]
	v_mfma_f32_16x16x32_bf16 v[8:11], v[76:79], v[84:87], v[8:11]
	v_mfma_f32_16x16x32_bf16 v[4:7], v[88:91], v[92:95], v[4:7]
	v_mfma_f32_16x16x32_bf16 v[8:11], v[88:91], v[96:99], v[8:11]
	v_mfma_f32_16x16x32_bf16 v[4:7], v[100:103], v[104:107], v[4:7]
	v_mfma_f32_16x16x32_bf16 v[8:11], v[100:103], v[108:111], v[8:11]
	v_mfma_f32_16x16x32_bf16 v[4:7], v[112:115], v[116:119], v[4:7]
	v_mfma_f32_16x16x32_bf16 v[8:11], v[112:115], v[120:123], v[8:11]
	v_mfma_f32_16x16x32_bf16 v[4:7], v[124:127], v[128:131], v[4:7]
	v_mfma_f32_16x16x32_bf16 v[8:11], v[124:127], v[132:135], v[8:11]
	v_mfma_f32_16x16x32_bf16 v[4:7], v[136:139], v[140:143], v[4:7]
	v_mfma_f32_16x16x32_bf16 v[8:11], v[136:139], v[144:147], v[8:11]
	v_mfma_f32_16x16x32_bf16 v[4:7], v[148:151], v[152:155], v[4:7]
	v_mfma_f32_16x16x32_bf16 v[8:11], v[148:151], v[156:159], v[8:11]
	v_mfma_f32_16x16x32_bf16 v[4:7], v[160:163], v[164:167], v[4:7]
	v_mfma_f32_16x16x32_bf16 v[8:11], v[160:163], v[168:171], v[8:11]
	s_barrier
	s_nop 7
	s_add_u32 s94, s80, 0x43752000
	s_addc_u32 s95, s81, 0
	s_lshl_b32 s91, s26, 14
	s_lshr_b32 s92, s90, 1
	s_lshl_b32 s92, s92, 12
	s_add_u32 s91, s91, s92
	s_and_b32 s92, s90, 1
	s_lshl_b32 s92, s92, 11
	s_add_u32 s91, s91, s92
	v_and_b32_e32 v72, 3, v200
	v_lshlrev_b32_e32 v72, 2, v72
	v_lshrrev_b32_e32 v73, 4, v200
	v_lshl_add_u32 v72, v73, 6, v72
	v_bfe_u32 v73, v200, 3, 1
	v_lshl_add_u32 v72, v73, 8, v72
	v_bfe_u32 v73, v200, 2, 1
	v_lshl_add_u32 v72, v73, 10, v72
	v_add_u32_e32 v72, s91, v72
	v_mov_b32_e32 v73, 0
	v_lshl_add_u64 v[72:73], s[94:95], 0, v[72:73]
	s_ashr_i32 s27, s26, 31
	s_lshl_b64 s[28:29], s[26:27], 14
	v_lshl_add_u64 v[0:1], s[28:29], 0, v[16:17]
	s_add_i32 s26, s26, s52
	s_add_i32 s0, s0, s1
	s_add_i32 s4, s4, s5
	v_lshl_add_u64 v[0:1], v[14:15], 0, v[0:1]
	s_cmpk_gt_i32 s26, 0x3ff
	flat_store_dword v[72:73], v4
	flat_store_dword v[72:73], v5 offset:16
	flat_store_dword v[72:73], v6 offset:32
	flat_store_dword v[72:73], v7 offset:48
	flat_store_dword v[72:73], v8 offset:512
	flat_store_dword v[72:73], v9 offset:528
	flat_store_dword v[72:73], v10 offset:544
	flat_store_dword v[72:73], v11 offset:560
	s_cbranch_scc0 .LBB0_765

.LBB0_894:
	s_or_b64 exec, exec, s[74:75]
	v_and_b32_e32 v76, 0x30, v221
	v_lshlrev_b32_e32 v76, 8, v76
	v_lshl_add_u32 v76, v200, 4, v76
	v_and_b32_e32 v148, -64, v221
	v_add_u32_e32 v148, s93, v148
	v_lshl_add_u32 v148, v148, 8, v76
	s_waitcnt lgkmcnt(0)
	v_lshl_add_u64 v[76:77], s[60:61], 0, v[148:149]
	flat_load_dwordx4 v[120:123], v[76:77]
	flat_load_dwordx4 v[116:119], v[76:77] offset:1024
	flat_load_dwordx4 v[80:83], v[76:77] offset:2048
	s_nop 0
	flat_load_dwordx4 v[76:79], v[76:77] offset:3072
	s_waitcnt lgkmcnt(0)
	s_barrier
	v_add_u32_e32 v254, 0x10000, v226
	ds_read_b128 v[84:87], v226
	ds_read_b128 v[88:91], v226 offset:16384
	ds_read_b128 v[92:95], v226 offset:32768
	ds_read_b128 v[96:99], v226 offset:49152
	ds_read_b128 v[100:103], v254
	ds_read_b128 v[104:107], v254 offset:16384
	ds_read_b128 v[108:111], v254 offset:32768
	ds_read_b128 v[112:115], v254 offset:49152
	ds_read_b128 v[234:237], v226 offset:1024
	ds_read_b128 v[238:241], v226 offset:17408
	ds_read_b128 v[242:245], v226 offset:33792
	ds_read_b128 v[246:249], v226 offset:50176
	ds_read_b128 v[250:253], v254 offset:1024
	s_waitcnt lgkmcnt(5)
	v_pk_add_f32 v[84:85], v[84:85], v[88:89]
	v_pk_add_f32 v[86:87], v[86:87], v[90:91]
	v_pk_add_f32 v[84:85], v[84:85], v[92:93]
	v_pk_add_f32 v[86:87], v[86:87], v[94:95]
	v_pk_add_f32 v[84:85], v[84:85], v[96:97]
	v_pk_add_f32 v[86:87], v[86:87], v[98:99]
	v_pk_add_f32 v[84:85], v[84:85], v[100:101]
	v_pk_add_f32 v[86:87], v[86:87], v[102:103]
	v_pk_add_f32 v[84:85], v[84:85], v[104:105]
	v_pk_add_f32 v[86:87], v[86:87], v[106:107]
	v_pk_add_f32 v[84:85], v[84:85], v[108:109]
	v_pk_add_f32 v[86:87], v[86:87], v[110:111]
	v_pk_add_f32 v[128:129], v[84:85], v[112:113]
	v_pk_add_f32 v[124:125], v[86:87], v[114:115]
	ds_read_b128 v[88:91], v254 offset:17408
	ds_read_b128 v[92:95], v254 offset:33792
	ds_read_b128 v[96:99], v254 offset:50176
	s_waitcnt lgkmcnt(3)
	v_pk_add_f32 v[234:235], v[234:235], v[238:239]
	v_pk_add_f32 v[236:237], v[236:237], v[240:241]
	v_pk_add_f32 v[234:235], v[234:235], v[242:243]
	v_pk_add_f32 v[236:237], v[236:237], v[244:245]
	v_pk_add_f32 v[234:235], v[234:235], v[246:247]
	v_pk_add_f32 v[236:237], v[236:237], v[248:249]
	v_pk_add_f32 v[234:235], v[234:235], v[250:251]
	v_pk_add_f32 v[236:237], v[236:237], v[252:253]
	s_waitcnt lgkmcnt(0)
	v_pk_add_f32 v[234:235], v[234:235], v[88:89]
	v_pk_add_f32 v[236:237], v[236:237], v[90:91]
	v_pk_add_f32 v[234:235], v[234:235], v[92:93]
	v_pk_add_f32 v[236:237], v[236:237], v[94:95]
	v_pk_add_f32 v[130:131], v[234:235], v[96:97]
	v_pk_add_f32 v[126:127], v[236:237], v[98:99]
